# v56 + up GEMM epilogue: eighth row-scale and the four column-scale loads issued with the first seven (one round trip fewer per unit)
# baseline (speedup 1.0000x reference)
;     __device__ __forceinline__ void operator()(f32x4 (&acc)[2][2][4][2], const Unit& u, int wr, int wc, int fr_in, int fq_in, int wid, LAS unsigned char* lds) const {
;     ...
;         float sv[8]; u32x4 cv[4];
; #pragma unroll
;         for (int k = 0; k < 8; ++k) sv[k] = sa[rowg + (k >> 2) * HALF + (k & 3) * 16 + fr] * (1.0f / 127.0f);
; #pragma unroll
;         for (int k = 0; k < 4; ++k) cv[k] = *(const u32x4*)(cmax + colw + 8 * fq + (k >> 1) * CBJ + (k & 1) * 4);
; #pragma unroll
;         for (int ai = 0; ai < 2; ++ai)
; #pragma unroll
;             for (int m = 0; m < 4; ++m) {
;                 const float s = sv[ai * 4 + m];
;                 float mx = 0.f;
; #pragma unroll
;                 for (int bj = 0; bj < 2; ++bj) {
;                     const v4i_t i0 = __builtin_bit_cast(v4i_t, acc[ai][bj][m][0]), i1 = __builtin_bit_cast(v4i_t, acc[ai][bj][m][1]);
;                     const u32x4 c0_ = cv[bj * 2], c1_ = cv[bj * 2 + 1];
;                     f32x4 v0, v1;
; #pragma unroll
;                     for (int j = 0; j < 4; ++j) { const float a = fmaxf((float)i0[j] * (s * __uint_as_float(c0_[j])), 0.f), b = fmaxf((float)i1[j] * (s * __uint_as_float(c1_[j])), 0.f); v0[j] = a * a; v1[j] = b * b; mx = fmaxf(mx, fmaxf(v0[j], v1[j])); }
;                     acc[ai][bj][m][0] = v0; acc[ai][bj][m][1] = v1;
;                 }
;                 mx = fmaxf(mx, __shfl_xor(mx, 16)); mx = fmaxf(mx, __shfl_xor(mx, 32));
;                 if (fq == 0) lmx[wc * 256 + wr * 64 + ai * HALF + m * 16 + fr] = mx;
.LBB0_1339:
	s_mov_b32 s0, s81
	s_mov_b32 s1, -1
	s_lshl_b32 s40, s52, 8
	v_mov_b32_e32 v130, v162
	v_mov_b32_e32 v166, v163
	s_add_i32 s0, s40, s47
	v_readlane_b32 s42, v249, 57
	v_add_u32_e32 v114, s0, v130
	v_ashrrev_i32_e32 v115, 31, v114
	v_readlane_b32 s43, v249, 58
	s_lshl_b32 s1, s53, 8
	s_or_b32 s82, s1, s84
	v_lshl_add_u64 v[116:117], v[114:115], 2, s[42:43]
	global_load_dword v115, v[116:117], off
	v_add_u32_e32 v116, 16, v114
	v_ashrrev_i32_e32 v117, 31, v116
	v_lshl_add_u64 v[116:117], v[116:117], 2, s[42:43]
	global_load_dword v176, v[116:117], off
	v_add_u32_e32 v116, 32, v114
	v_ashrrev_i32_e32 v117, 31, v116
	v_lshl_add_u64 v[116:117], v[116:117], 2, s[42:43]
	global_load_dword v175, v[116:117], off
	v_add_u32_e32 v116, 48, v114
	v_ashrrev_i32_e32 v117, 31, v116
	v_lshl_add_u64 v[116:117], v[116:117], 2, s[42:43]
	global_load_dword v174, v[116:117], off
	v_add_u32_e32 v116, 0x80, v114
	v_ashrrev_i32_e32 v117, 31, v116
	v_lshl_add_u64 v[116:117], v[116:117], 2, s[42:43]
	global_load_dword v173, v[116:117], off
	v_add_u32_e32 v116, 0x90, v114
	v_ashrrev_i32_e32 v117, 31, v116
	v_lshl_add_u64 v[116:117], v[116:117], 2, s[42:43]
	global_load_dword v172, v[116:117], off
	v_add_u32_e32 v116, 0xa0, v114
	v_add_u32_e32 v114, 0xb0, v114
	v_ashrrev_i32_e32 v117, 31, v116
	s_ashr_i32 s83, s82, 31
	v_lshl_add_u64 v[116:117], v[116:117], 2, s[42:43]
	v_lshlrev_b32_e32 v160, 3, v166
	v_ashrrev_i32_e32 v161, 31, v160
	global_load_dword v171, v[116:117], off
	v_mov_b32_e32 v182, v114
	v_ashrrev_i32_e32 v183, 31, v114
	v_lshl_add_u64 v[182:183], v[182:183], 2, s[42:43]
	global_load_dword v167, v[182:183], off
	s_lshl_b64 s[98:99], s[82:83], 2
	s_add_u32 s98, s35, s98
	s_addc_u32 s99, s38, s99
	v_lshl_add_u64 v[184:185], v[160:161], 2, s[98:99]
	global_load_dwordx4 v[126:129], v[184:185], off offset:16
	global_load_dwordx4 v[136:139], v[184:185], off
	global_load_dwordx4 v[186:189], v[184:185], off offset:144
	global_load_dwordx4 v[190:193], v[184:185], off offset:128
	v_cvt_f32_i32_e32 v144, v144
	v_cvt_f32_i32_e32 v145, v145
	v_cvt_f32_i32_e32 v140, v140
	v_cvt_f32_i32_e32 v141, v141
	v_cvt_f32_i32_e32 v146, v146
	v_cvt_f32_i32_e32 v147, v147
	v_cvt_f32_i32_e32 v142, v142
	v_cvt_f32_i32_e32 v143, v143
	v_cvt_f32_i32_e32 v132, v132
	v_cvt_f32_i32_e32 v133, v133
	v_cvt_f32_i32_e32 v122, v122
	v_cvt_f32_i32_e32 v123, v123
	v_cvt_f32_i32_e32 v134, v134
	v_cvt_f32_i32_e32 v124, v124
	v_cvt_f32_i32_e32 v135, v135
	v_cvt_f32_i32_e32 v125, v125
	v_and_b32_e32 v169, 64, v204
	v_xor_b32_e32 v168, 16, v204
	v_add_u32_e32 v170, 64, v169
	v_cmp_lt_i32_e32 vcc, v168, v170
	s_waitcnt vmcnt(5)
	v_mul_f32_e32 v177, 0x3c010204, v115
	v_ashrrev_i32_e32 v115, 31, v114
	v_lshl_add_u64 v[114:115], v[114:115], 2, s[42:43]
	s_lshl_b64 s[42:43], s[82:83], 2
	s_add_u32 s42, s35, s42
	s_addc_u32 s43, s38, s43
	v_lshl_add_u64 v[118:119], v[160:161], 2, s[42:43]
	s_nop 0
	s_nop 0
	v_cndmask_b32_e32 v168, v204, v168, vcc
	v_lshlrev_b32_e32 v169, 2, v168
	v_xor_b32_e32 v168, 32, v204
	v_cmp_lt_i32_e32 vcc, v168, v170
	s_waitcnt vmcnt(2)
	v_mul_f32_e32 v178, v177, v136
	v_mul_f32_e32 v179, v177, v137
	v_mul_f32_e32 v144, v178, v144
	v_mul_f32_e32 v178, v177, v126
	v_mul_f32_e32 v145, v179, v145
	v_mul_f32_e32 v179, v177, v127
	v_mul_f32_e32 v140, v178, v140
	v_mul_f32_e32 v141, v179, v141
	v_max_f32_e32 v144, 0, v144
	v_max_f32_e32 v140, 0, v140
	v_max_f32_e32 v145, 0, v145
	v_max_f32_e32 v141, 0, v141
	v_mul_f32_e32 v144, v144, v144
	v_mul_f32_e32 v140, v140, v140
	v_mul_f32_e32 v145, v145, v145
	v_mul_f32_e32 v141, v141, v141
	v_max_f32_e32 v178, v144, v140
	v_max_f32_e32 v179, v145, v141
	v_max3_f32 v178, v178, 0, v179
	v_mul_f32_e32 v179, v177, v138
	v_mul_f32_e32 v180, v177, v139
	v_mul_f32_e32 v146, v179, v146
	v_mul_f32_e32 v179, v177, v128
	v_mul_f32_e32 v147, v180, v147
	v_mul_f32_e32 v180, v177, v129
	v_mul_f32_e32 v142, v179, v142
	v_mul_f32_e32 v143, v180, v143
	v_max_f32_e32 v146, 0, v146
	v_max_f32_e32 v142, 0, v142
	v_max_f32_e32 v147, 0, v147
	v_max_f32_e32 v143, 0, v143
	v_mul_f32_e32 v146, v146, v146
	v_mul_f32_e32 v142, v142, v142
	v_mul_f32_e32 v147, v147, v147
	v_mul_f32_e32 v143, v143, v143
	v_max_f32_e32 v179, v146, v142
	v_max_f32_e32 v180, v147, v143
	v_max3_f32 v178, v178, v179, v180
	s_waitcnt vmcnt(0)
	v_mov_b32_e32 v114, v186
	v_mov_b32_e32 v115, v187
	v_mov_b32_e32 v116, v188
	v_mov_b32_e32 v117, v189
	v_mov_b32_e32 v118, v190
	v_mov_b32_e32 v119, v191
	v_mov_b32_e32 v120, v192
	v_mov_b32_e32 v121, v193
	v_mul_f32_e32 v179, v177, v118
	v_mul_f32_e32 v180, v177, v119
	v_mul_f32_e32 v132, v179, v132
	v_mul_f32_e32 v179, v177, v114
	v_mul_f32_e32 v133, v180, v133
	v_mul_f32_e32 v180, v177, v115
	v_mul_f32_e32 v122, v179, v122
	v_mul_f32_e32 v123, v180, v123
	v_max_f32_e32 v132, 0, v132
	v_max_f32_e32 v122, 0, v122
	v_max_f32_e32 v133, 0, v133
	v_max_f32_e32 v123, 0, v123
	v_mul_f32_e32 v132, v132, v132
	v_mul_f32_e32 v122, v122, v122
	v_mul_f32_e32 v133, v133, v133
	v_mul_f32_e32 v123, v123, v123
	v_max_f32_e32 v179, v132, v122
	v_max_f32_e32 v180, v133, v123
	v_max3_f32 v178, v178, v179, v180
	v_mul_f32_e32 v179, v177, v120
	v_mul_f32_e32 v134, v179, v134
	v_mul_f32_e32 v179, v177, v116
	v_mul_f32_e32 v180, v177, v121
	v_mul_f32_e32 v177, v177, v117
	v_mul_f32_e32 v124, v179, v124
	v_mul_f32_e32 v135, v180, v135
	v_mul_f32_e32 v125, v177, v125
	v_max_f32_e32 v134, 0, v134
	v_max_f32_e32 v124, 0, v124
	v_max_f32_e32 v135, 0, v135
	v_max_f32_e32 v125, 0, v125
	v_mul_f32_e32 v134, v134, v134
	v_mul_f32_e32 v124, v124, v124
	v_mul_f32_e32 v135, v135, v135
	v_mul_f32_e32 v125, v125, v125
	v_max_f32_e32 v179, v134, v124
	v_max_f32_e32 v177, v135, v125
	v_max3_f32 v177, v178, v179, v177
	ds_bpermute_b32 v178, v169, v177
	v_cndmask_b32_e32 v168, v204, v168, vcc
	v_lshlrev_b32_e32 v170, 2, v168
	v_cmp_eq_u32_e32 vcc, 0, v166
	v_lshl_add_u32 v168, v130, 2, s85
	s_waitcnt lgkmcnt(0)
	v_max_f32_e32 v178, v178, v178
	v_max_f32_e32 v177, v177, v178
	ds_bpermute_b32 v178, v170, v177
	s_and_saveexec_b64 s[42:43], vcc
	s_cbranch_execz .LBB0_1341
	s_waitcnt lgkmcnt(0)
	v_max_f32_e32 v178, v178, v178
	v_max_f32_e32 v177, v177, v177
	v_max_f32_e32 v177, v177, v178
	ds_write_b32 v168, v177
